# LRU carry: serial per-wave LDS-dependent loop replaced by 14 independent LDS reads + 7 predicated fmas (same op order), on top of all wait-count fixes
# speedup vs baseline: 1.0032x; 1.0018x over previous
; __device__ __forceinline__ float bf2f(u16 b) { return __uint_as_float(((unsigned)b) << 16); }
; __device__ __forceinline__ void lru_phase(const Args& A, unsigned char* smem, const bool dry) {
;     ...
;                 { bf16x8 Af[2];
; #pragma unroll
;                     for (int ks = 0; ks < 2; ++ks) Af[ks] = *(const bf16x8*)(ub + (16 * wave + r16) * 72 + ks * 32 + q4 * 8);
; #pragma unroll
;                     for (int dt = 0; dt < 4; ++dt) { const int d = 16 * dt + r16;
;                         f32x4 ga = (f32x4){0.f, 0.f, 0.f, 0.f}, gx = (f32x4){0.f, 0.f, 0.f, 0.f};
; #pragma unroll
;                         for (int ks = 0; ks < 2; ++ks) { const bf16x8 Ba = *(const bf16x8*)(wT + (d) * 72 + ks * 32 + q4 * 8); const bf16x8 Bx = *(const bf16x8*)(wT + (64 + d) * 72 + ks * 32 + q4 * 8);
;                             ga = __builtin_amdgcn_mfma_f32_16x16x32_bf16(Af[ks], Ba, ga, 0, 0, 0); gx = __builtin_amdgcn_mfma_f32_16x16x32_bf16(Af[ks], Bx, gx, 0, 0, 0); }
; #pragma unroll
;                         for (int j = 0; j < 4; ++j) { const int i = 16 * wave + 4 * q4 + j;
;                             const float ea = 1.0f + __expf(-(ga[j] + ba[dt])), ex = 1.0f + __expf(-(gx[j] + bx[dt])); const float rab = __builtin_amdgcn_rcpf(ea * ex);
;                             const float rg = rab * ex, ig = rab * ea;
;                             const float la = -8.0f * rg * sp[dt]; const float av = __expf(la); const float v2 = 2.0f * la;
;                             const float em = (v2 > -0.02f) ? v2 * (1.0f + v2 * (0.5f + v2 * (1.0f / 6.0f))) : (av * av - 1.0f);
;                             aL[i * 64 + d] = av; bL[i * 64 + d] = sqrtf(-em) * ig * bf2f(ub[i * 72 + d]); } } }
.LBB0_509:
	s_waitcnt lgkmcnt(0)
	s_barrier
	ds_read_b128 v[24:27], v133 offset:18432
	ds_read_b128 v[32:35], v76
	ds_read_b128 v[28:31], v133 offset:18496
	ds_read_b128 v[36:39], v76 offset:64
	ds_read_b128 v[60:63], v76 offset:9216
	ds_read_b128 v[154:157], v76 offset:9280
	s_waitcnt lgkmcnt(4)
	v_mfma_f32_16x16x32_bf16 v[32:35], v[24:27], v[32:35], 0
	s_waitcnt lgkmcnt(1)
	v_mfma_f32_16x16x32_bf16 v[60:63], v[24:27], v[60:63], 0
	v_mfma_f32_16x16x32_bf16 v[36:39], v[28:31], v[36:39], v[32:35]
	s_waitcnt lgkmcnt(0)
	v_mfma_f32_16x16x32_bf16 v[32:35], v[28:31], v[154:157], v[60:63]
	s_nop 5
	v_add_f32_e32 v36, v42, v36
	s_nop 0
	v_add_f32_e32 v32, v145, v32
	v_add_f32_e32 v47, v42, v37
	v_mul_f32_e32 v36, 0xbfb8aa3b, v36
	v_mul_f32_e32 v32, 0xbfb8aa3b, v32
	v_add_f32_e32 v33, v145, v33
	v_exp_f32_e32 v36, v36
	v_exp_f32_e32 v37, v32
	v_mul_f32_e32 v32, 0xbfb8aa3b, v47
	v_mul_f32_e32 v33, 0xbfb8aa3b, v33
	v_exp_f32_e32 v32, v32
	v_exp_f32_e32 v33, v33
	v_pk_add_f32 v[60:61], v[36:37], 1.0 op_sel_hi:[1,0]
	v_add_f32_e32 v34, v145, v34
	v_mul_f32_e32 v36, v60, v61
	v_pk_add_f32 v[62:63], v[32:33], 1.0 op_sel_hi:[1,0]
	v_rcp_f32_e32 v37, v36
	v_mul_f32_e32 v32, v62, v63
	v_rcp_f32_e32 v36, v32
	v_mul_f32_e32 v34, 0xbfb8aa3b, v34
	v_mul_f32_e32 v154, v60, v37
	v_mov_b32_e32 v60, v63
	v_pk_mul_f32 v[32:33], v[60:61], v[36:37]
	v_mul_f32_e32 v36, v62, v36
	v_pk_mul_f32 v[32:33], v[32:33], s[14:15] op_sel_hi:[1,0]
	v_add_f32_e32 v35, v145, v35
	v_pk_mul_f32 v[60:61], v[52:53], v[32:33]
	v_mul_f32_e32 v35, 0xbfb8aa3b, v35
	v_mul_f32_e32 v32, 0x3fb8aa3b, v61
	v_exp_f32_e32 v63, v32
	v_pk_add_f32 v[32:33], v[60:61], v[60:61]
	v_mul_f32_e32 v60, 0x3fb8aa3b, v60
	v_fma_f32 v37, v33, s41, 0.5
	v_fma_f32 v37, v33, v37, 1.0
	v_mul_f32_e32 v37, v33, v37
	v_fma_f32 v47, v63, v63, -1.0
	v_cmp_lt_f32_e32 vcc, s42, v33
	v_exp_f32_e32 v60, v60
	v_exp_f32_e32 v35, v35
	v_cndmask_b32_e32 v33, v47, v37, vcc
	v_mul_f32_e64 v37, -v33, s44
	v_cmp_lt_f32_e32 vcc, s43, v33
	s_nop 1
	v_cndmask_b32_e64 v155, -v33, v37, vcc
	v_sqrt_f32_e32 v156, v155
	ds_read_u16 v158, v134 offset:18432
	ds_read_u16 v157, v134 offset:18576
	ds_read_u16 v33, v134 offset:18464
	ds_read_u16 v47, v134 offset:18608
	ds_read_u16 v37, v134 offset:18496
	ds_read_u16 v49, v134 offset:18640
	ds_read_u16 v61, v134 offset:18672
	ds_read_u16 v159, v134 offset:18528
	ds_write_b32 v77, v63 offset:36864
	s_waitcnt lgkmcnt(8)
	v_lshlrev_b32_e32 v158, 16, v158
	v_add_u32_e32 v62, -1, v156
	v_fma_f32 v63, -v62, v156, v155
	v_cmp_ge_f32_e64 s[10:11], 0, v63
	v_add_u32_e32 v63, 1, v156
	s_waitcnt lgkmcnt(6)
	v_lshlrev_b32_e32 v33, 16, v33
	v_cndmask_b32_e64 v62, v156, v62, s[10:11]
	v_fma_f32 v156, -v63, v156, v155
	v_cmp_lt_f32_e64 s[10:11], 0, v156
	s_waitcnt lgkmcnt(4)
	v_lshlrev_b32_e32 v37, 16, v37
	v_cndmask_b32_e64 v62, v62, v63, s[10:11]
	v_mul_f32_e32 v63, 0x37800000, v62
	v_cndmask_b32_e32 v62, v62, v63, vcc
	v_cmp_class_f32_e32 vcc, v155, v135
	v_fma_f32 v63, v32, s41, 0.5
	v_fma_f32 v63, v32, v63, 1.0
	v_cndmask_b32_e32 v62, v62, v155, vcc
	v_mul_f32_e32 v62, v154, v62
	v_mul_f32_e32 v63, v32, v63
	v_fma_f32 v154, v60, v60, -1.0
	v_cmp_lt_f32_e32 vcc, s42, v32
	v_mul_f32_e32 v62, v62, v158
	ds_write_b32 v78, v62
	ds_write_b32 v79, v60 offset:36864
	v_cndmask_b32_e32 v32, v154, v63, vcc
	v_mul_f32_e64 v63, -v32, s44
	v_cmp_lt_f32_e32 vcc, s43, v32
	s_nop 1
	v_cndmask_b32_e64 v32, -v32, v63, vcc
	v_sqrt_f32_e32 v63, v32
	s_nop 0
	v_add_u32_e32 v60, -1, v63
	v_fma_f32 v62, -v60, v63, v32
	v_cmp_ge_f32_e64 s[10:11], 0, v62
	v_add_u32_e32 v62, 1, v63
	s_nop 0
	v_cndmask_b32_e64 v60, v63, v60, s[10:11]
	v_fma_f32 v63, -v62, v63, v32
	v_cmp_lt_f32_e64 s[10:11], 0, v63
	v_exp_f32_e32 v63, v34
	v_add_f32_e32 v34, v42, v39
	v_cndmask_b32_e64 v60, v60, v62, s[10:11]
	v_mul_f32_e32 v62, 0x37800000, v60
	v_cndmask_b32_e32 v60, v60, v62, vcc
	v_cmp_class_f32_e32 vcc, v32, v135
	v_mul_f32_e32 v34, 0xbfb8aa3b, v34
	v_exp_f32_e32 v34, v34
	v_cndmask_b32_e32 v32, v60, v32, vcc
	v_mul_f32_e32 v32, v36, v32
	v_lshlrev_b32_e32 v36, 16, v157
	v_mul_f32_e32 v32, v32, v36
	v_add_f32_e32 v36, v42, v38
	v_mul_f32_e32 v36, 0xbfb8aa3b, v36
	v_exp_f32_e32 v62, v36
	v_pk_add_f32 v[154:155], v[34:35], 1.0 op_sel_hi:[1,0]
	ds_write_b32 v83, v32
	v_mul_f32_e32 v34, v154, v155
	v_pk_add_f32 v[38:39], v[62:63], 1.0 op_sel_hi:[1,0]
	v_rcp_f32_e32 v62, v34
	v_mul_f32_e32 v36, v38, v39
	v_rcp_f32_e32 v63, v36
	s_nop 0
	v_mul_f32_e32 v36, v38, v63
	v_mov_b32_e32 v38, v155
	v_pk_mul_f32 v[34:35], v[38:39], v[62:63]
	v_mul_f32_e32 v62, v154, v62
	v_pk_mul_f32 v[34:35], v[34:35], s[14:15] op_sel_hi:[1,0]
	s_nop 0
	v_pk_mul_f32 v[38:39], v[52:53], v[34:35]
	s_nop 0
	v_mul_f32_e32 v32, 0x3fb8aa3b, v39
	v_exp_f32_e32 v35, v32
	v_pk_add_f32 v[156:157], v[38:39], v[38:39]
	v_fma_f32 v34, v35, v35, -1.0
	v_fma_f32 v32, v157, s41, 0.5
	v_fma_f32 v32, v157, v32, 1.0
	v_mul_f32_e32 v32, v157, v32
	v_cmp_lt_f32_e32 vcc, s42, v157
	s_nop 1
	v_cndmask_b32_e32 v32, v34, v32, vcc
	v_mul_f32_e64 v34, -v32, s44
	v_cmp_lt_f32_e32 vcc, s43, v32
	s_nop 1
	v_cndmask_b32_e64 v39, -v32, v34, vcc
	v_sqrt_f32_e32 v60, v39
	ds_read_u16 v63, v134 offset:18720
	ds_read_u16 v155, v134 offset:18864
	ds_read_u16 v158, v134 offset:18752
	ds_read_u16 v172, v134 offset:18896
	ds_read_u16 v173, v134 offset:18784
	ds_read_u16 v174, v134 offset:18928
	ds_read_u16 v32, v134 offset:18960
	ds_read_u16 v34, v134 offset:18816
	ds_write_b32 v84, v35 offset:36864
	s_waitcnt lgkmcnt(8)
; __device__ __forceinline__ float bf2f(u16 b) { return __uint_as_float(((unsigned)b) << 16); }
; __device__ __forceinline__ void lru_phase(const Args& A, unsigned char* smem, const bool dry) {
;     ...
;                     for (int dt = 0; dt < 4; ++dt) { const int d = 16 * dt + r16;
;                         f32x4 ga = (f32x4){0.f, 0.f, 0.f, 0.f}, gx = (f32x4){0.f, 0.f, 0.f, 0.f};
; #pragma unroll
;                         for (int ks = 0; ks < 2; ++ks) { const bf16x8 Ba = *(const bf16x8*)(wT + (d) * 72 + ks * 32 + q4 * 8); const bf16x8 Bx = *(const bf16x8*)(wT + (64 + d) * 72 + ks * 32 + q4 * 8);
;                             ga = __builtin_amdgcn_mfma_f32_16x16x32_bf16(Af[ks], Ba, ga, 0, 0, 0); gx = __builtin_amdgcn_mfma_f32_16x16x32_bf16(Af[ks], Bx, gx, 0, 0, 0); }
; #pragma unroll
;                         for (int j = 0; j < 4; ++j) { const int i = 16 * wave + 4 * q4 + j;
;                             const float ea = 1.0f + __expf(-(ga[j] + ba[dt])), ex = 1.0f + __expf(-(gx[j] + bx[dt])); const float rab = __builtin_amdgcn_rcpf(ea * ex);
;                             const float rg = rab * ex, ig = rab * ea;
;                             const float la = -8.0f * rg * sp[dt]; const float av = __expf(la); const float v2 = 2.0f * la;
;                             const float em = (v2 > -0.02f) ? v2 * (1.0f + v2 * (0.5f + v2 * (1.0f / 6.0f))) : (av * av - 1.0f);
;                             aL[i * 64 + d] = av; bL[i * 64 + d] = sqrtf(-em) * ig * bf2f(ub[i * 72 + d]); } } }
	v_lshlrev_b32_e32 v63, 16, v63
	v_add_u32_e32 v35, -1, v60
	v_fma_f32 v154, -v35, v60, v39
	v_cmp_ge_f32_e64 s[10:11], 0, v154
	v_add_u32_e32 v154, 1, v60
	s_nop 0
	v_cndmask_b32_e64 v35, v60, v35, s[10:11]
	v_fma_f32 v60, -v154, v60, v39
	v_cmp_lt_f32_e64 s[10:11], 0, v60
	s_nop 1
	v_cndmask_b32_e64 v35, v35, v154, s[10:11]
	v_mul_f32_e32 v60, 0x37800000, v35
	v_cndmask_b32_e32 v35, v35, v60, vcc
	v_cmp_class_f32_e32 vcc, v39, v135
	s_nop 1
	v_cndmask_b32_e32 v35, v35, v39, vcc
	v_mul_f32_e32 v35, v36, v35
	v_mul_f32_e32 v36, 0x3fb8aa3b, v38
	v_exp_f32_e32 v36, v36
	v_fma_f32 v38, v156, s41, 0.5
	v_fma_f32 v38, v156, v38, 1.0
	v_mul_f32_e32 v38, v156, v38
	v_fma_f32 v39, v36, v36, -1.0
	v_cmp_lt_f32_e32 vcc, s42, v156
	v_mul_f32_e32 v35, v35, v63
	ds_write_b32 v85, v35
	ds_write_b32 v86, v36 offset:36864
	v_cndmask_b32_e32 v38, v39, v38, vcc
	v_mul_f32_e64 v39, -v38, s44
	v_cmp_lt_f32_e32 vcc, s43, v38
	s_nop 1
	v_cndmask_b32_e64 v38, -v38, v39, vcc
	v_sqrt_f32_e32 v39, v38
	s_nop 0
	v_add_u32_e32 v35, -1, v39
	v_fma_f32 v36, -v35, v39, v38
	v_cmp_ge_f32_e64 s[10:11], 0, v36
	v_add_u32_e32 v36, 1, v39
	s_nop 0
	v_cndmask_b32_e64 v35, v39, v35, s[10:11]
	v_fma_f32 v39, -v36, v39, v38
	v_cmp_lt_f32_e64 s[10:11], 0, v39
	s_nop 1
	v_cndmask_b32_e64 v35, v35, v36, s[10:11]
	v_mul_f32_e32 v36, 0x37800000, v35
	v_cndmask_b32_e32 v35, v35, v36, vcc
	v_cmp_class_f32_e32 vcc, v38, v135
	s_waitcnt lgkmcnt(9)
	v_lshlrev_b32_e32 v36, 16, v155
	v_cndmask_b32_e32 v35, v35, v38, vcc
	v_mul_f32_e32 v35, v62, v35
	v_mul_f32_e32 v35, v35, v36
	ds_write_b32 v87, v35
	ds_read_b128 v[154:157], v88
	ds_read_b128 v[160:163], v88 offset:64
	ds_read_b128 v[164:167], v88 offset:9216
	ds_read_b128 v[168:171], v88 offset:9280
	s_waitcnt lgkmcnt(3)
	v_mfma_f32_16x16x32_bf16 v[154:157], v[24:27], v[154:157], 0
	s_waitcnt lgkmcnt(1)
	v_mfma_f32_16x16x32_bf16 v[164:167], v[24:27], v[164:167], 0
	v_mfma_f32_16x16x32_bf16 v[154:157], v[28:31], v[160:163], v[154:157]
	s_waitcnt lgkmcnt(0)
	v_mfma_f32_16x16x32_bf16 v[160:163], v[28:31], v[168:171], v[164:167]
	s_nop 5
	v_add_f32_e32 v35, v146, v154
	v_mul_f32_e32 v35, 0xbfb8aa3b, v35
	v_exp_f32_e32 v38, v35
	v_add_f32_e32 v35, v147, v160
	v_mul_f32_e32 v35, 0xbfb8aa3b, v35
	v_exp_f32_e32 v39, v35
	v_add_f32_e32 v35, v146, v155
	v_mul_f32_e32 v35, 0xbfb8aa3b, v35
	v_exp_f32_e32 v62, v35
	v_add_f32_e32 v35, v147, v161
	v_mul_f32_e32 v35, 0xbfb8aa3b, v35
	v_exp_f32_e32 v63, v35
	v_pk_add_f32 v[38:39], v[38:39], 1.0 op_sel_hi:[1,0]
	v_pk_add_f32 v[62:63], v[62:63], 1.0 op_sel_hi:[1,0]
	v_mul_f32_e32 v35, v38, v39
	v_rcp_f32_e32 v155, v35
	v_mul_f32_e32 v35, v62, v63
	v_rcp_f32_e32 v154, v35
	v_mul_f32_e32 v35, v38, v155
	v_mov_b32_e32 v38, v63
	v_pk_mul_f32 v[38:39], v[38:39], v[154:155]
	v_mul_f32_e32 v62, v62, v154
	v_pk_mul_f32 v[38:39], v[38:39], s[14:15] op_sel_hi:[1,0]
	s_nop 0
	v_pk_mul_f32 v[38:39], v[54:55], v[38:39]
	s_nop 0
	v_mul_f32_e32 v36, 0x3fb8aa3b, v39
	v_exp_f32_e32 v36, v36
	v_pk_add_f32 v[160:161], v[38:39], v[38:39]
	v_fma_f32 v60, v36, v36, -1.0
	v_fma_f32 v39, v161, s41, 0.5
	v_fma_f32 v39, v161, v39, 1.0
	v_mul_f32_e32 v39, v161, v39
	v_cmp_lt_f32_e32 vcc, s42, v161
	ds_write_b32 v89, v36 offset:36928
	s_nop 0
	v_cndmask_b32_e32 v39, v60, v39, vcc
	v_mul_f32_e64 v60, -v39, s44
	v_cmp_lt_f32_e32 vcc, s43, v39
	s_nop 1
	v_cndmask_b32_e64 v39, -v39, v60, vcc
	v_sqrt_f32_e32 v60, v39
	s_nop 0
	v_add_u32_e32 v36, -1, v60
	v_fma_f32 v63, -v36, v60, v39
	v_cmp_ge_f32_e64 s[10:11], 0, v63
	v_add_u32_e32 v63, 1, v60
	s_nop 0
	v_cndmask_b32_e64 v36, v60, v36, s[10:11]
	v_fma_f32 v60, -v63, v60, v39
	v_cmp_lt_f32_e64 s[10:11], 0, v60
	s_nop 1
	v_cndmask_b32_e64 v36, v36, v63, s[10:11]
	v_mul_f32_e32 v60, 0x37800000, v36
	v_cndmask_b32_e32 v36, v36, v60, vcc
	v_cmp_class_f32_e32 vcc, v39, v135
	s_nop 1
	v_cndmask_b32_e32 v36, v36, v39, vcc
	v_mul_f32_e32 v35, v35, v36
	v_mul_f32_e32 v36, 0x3fb8aa3b, v38
	v_exp_f32_e32 v36, v36
	v_fma_f32 v38, v160, s41, 0.5
	v_fma_f32 v38, v160, v38, 1.0
	v_mul_f32_e32 v38, v160, v38
	v_fma_f32 v39, v36, v36, -1.0
	v_cmp_lt_f32_e32 vcc, s42, v160
	v_mul_f32_e32 v33, v35, v33
	ds_write_b32 v90, v33
	ds_write_b32 v91, v36 offset:36928
	v_cndmask_b32_e32 v38, v39, v38, vcc
	v_mul_f32_e64 v39, -v38, s44
	v_cmp_lt_f32_e32 vcc, s43, v38
	s_nop 1
	v_cndmask_b32_e64 v38, -v38, v39, vcc
	v_sqrt_f32_e32 v39, v38
	s_nop 0
	v_add_u32_e32 v33, -1, v39
	v_fma_f32 v35, -v33, v39, v38
	v_cmp_ge_f32_e64 s[10:11], 0, v35
	v_add_u32_e32 v35, 1, v39
	v_fma_f32 v36, -v35, v39, v38
	v_cndmask_b32_e64 v33, v39, v33, s[10:11]
	v_cmp_lt_f32_e64 s[10:11], 0, v36
	s_nop 1
	v_cndmask_b32_e64 v33, v33, v35, s[10:11]
	v_mul_f32_e32 v35, 0x37800000, v33
	v_cndmask_b32_e32 v33, v33, v35, vcc
	v_cmp_class_f32_e32 vcc, v38, v135
	v_lshlrev_b32_e32 v35, 16, v47
	v_lshlrev_b32_e32 v47, 16, v158
	v_cndmask_b32_e32 v33, v33, v38, vcc
	v_mul_f32_e32 v33, v62, v33
	v_mul_f32_e32 v33, v33, v35
	v_add_f32_e32 v35, v146, v156
	v_mul_f32_e32 v35, 0xbfb8aa3b, v35
	v_exp_f32_e32 v38, v35
	v_add_f32_e32 v35, v147, v162
	v_mul_f32_e32 v35, 0xbfb8aa3b, v35
	v_exp_f32_e32 v39, v35
	v_add_f32_e32 v35, v146, v157
	v_mul_f32_e32 v35, 0xbfb8aa3b, v35
	v_exp_f32_e32 v62, v35
	v_add_f32_e32 v35, v147, v163
	v_mul_f32_e32 v35, 0xbfb8aa3b, v35
	v_exp_f32_e32 v63, v35
	v_pk_add_f32 v[38:39], v[38:39], 1.0 op_sel_hi:[1,0]
	ds_write_b32 v92, v33
	v_mul_f32_e32 v35, v38, v39
	v_pk_add_f32 v[62:63], v[62:63], 1.0 op_sel_hi:[1,0]
	v_rcp_f32_e32 v155, v35
	v_mul_f32_e32 v35, v62, v63
	v_rcp_f32_e32 v154, v35
	v_mul_f32_e32 v33, v38, v155
	v_mov_b32_e32 v38, v63
	v_pk_mul_f32 v[38:39], v[38:39], v[154:155]
	v_mul_f32_e32 v60, v62, v154
; __device__ __forceinline__ float bf2f(u16 b) { return __uint_as_float(((unsigned)b) << 16); }
; __device__ __forceinline__ void lru_phase(const Args& A, unsigned char* smem, const bool dry) {
;     ...
;                     for (int dt = 0; dt < 4; ++dt) { const int d = 16 * dt + r16;
;                         f32x4 ga = (f32x4){0.f, 0.f, 0.f, 0.f}, gx = (f32x4){0.f, 0.f, 0.f, 0.f};
; #pragma unroll
;                         for (int ks = 0; ks < 2; ++ks) { const bf16x8 Ba = *(const bf16x8*)(wT + (d) * 72 + ks * 32 + q4 * 8); const bf16x8 Bx = *(const bf16x8*)(wT + (64 + d) * 72 + ks * 32 + q4 * 8);
;                             ga = __builtin_amdgcn_mfma_f32_16x16x32_bf16(Af[ks], Ba, ga, 0, 0, 0); gx = __builtin_amdgcn_mfma_f32_16x16x32_bf16(Af[ks], Bx, gx, 0, 0, 0); }
; #pragma unroll
;                         for (int j = 0; j < 4; ++j) { const int i = 16 * wave + 4 * q4 + j;
;                             const float ea = 1.0f + __expf(-(ga[j] + ba[dt])), ex = 1.0f + __expf(-(gx[j] + bx[dt])); const float rab = __builtin_amdgcn_rcpf(ea * ex);
;                             const float rg = rab * ex, ig = rab * ea;
;                             const float la = -8.0f * rg * sp[dt]; const float av = __expf(la); const float v2 = 2.0f * la;
;                             const float em = (v2 > -0.02f) ? v2 * (1.0f + v2 * (0.5f + v2 * (1.0f / 6.0f))) : (av * av - 1.0f);
;                             aL[i * 64 + d] = av; bL[i * 64 + d] = sqrtf(-em) * ig * bf2f(ub[i * 72 + d]); } } }
	v_pk_mul_f32 v[38:39], v[38:39], s[14:15] op_sel_hi:[1,0]
	s_nop 0
	v_pk_mul_f32 v[38:39], v[54:55], v[38:39]
	s_nop 0
	v_mul_f32_e32 v35, 0x3fb8aa3b, v39
	v_exp_f32_e32 v35, v35
	v_pk_add_f32 v[156:157], v[38:39], v[38:39]
	v_fma_f32 v39, v35, v35, -1.0
	v_fma_f32 v36, v157, s41, 0.5
	v_fma_f32 v36, v157, v36, 1.0
	v_mul_f32_e32 v36, v157, v36
	v_cmp_lt_f32_e32 vcc, s42, v157
	ds_write_b32 v93, v35 offset:36928
	s_nop 0
	v_cndmask_b32_e32 v36, v39, v36, vcc
	v_mul_f32_e64 v39, -v36, s44
	v_cmp_lt_f32_e32 vcc, s43, v36
	s_nop 1
	v_cndmask_b32_e64 v36, -v36, v39, vcc
	v_sqrt_f32_e32 v39, v36
	s_nop 0
	v_add_u32_e32 v35, -1, v39
	v_fma_f32 v62, -v35, v39, v36
	v_cmp_ge_f32_e64 s[10:11], 0, v62
	v_add_u32_e32 v62, 1, v39
	s_nop 0
	v_cndmask_b32_e64 v35, v39, v35, s[10:11]
	v_fma_f32 v39, -v62, v39, v36
	v_cmp_lt_f32_e64 s[10:11], 0, v39
	s_nop 1
	v_cndmask_b32_e64 v35, v35, v62, s[10:11]
	v_mul_f32_e32 v39, 0x37800000, v35
	v_cndmask_b32_e32 v35, v35, v39, vcc
	v_cmp_class_f32_e32 vcc, v36, v135
	s_nop 1
	v_cndmask_b32_e32 v35, v35, v36, vcc
	v_mul_f32_e32 v33, v33, v35
	v_mul_f32_e32 v35, 0x3fb8aa3b, v38
	v_exp_f32_e32 v35, v35
	v_fma_f32 v36, v156, s41, 0.5
	v_fma_f32 v36, v156, v36, 1.0
	v_mul_f32_e32 v36, v156, v36
	v_fma_f32 v38, v35, v35, -1.0
	v_cmp_lt_f32_e32 vcc, s42, v156
	v_mul_f32_e32 v33, v33, v47
	ds_write_b32 v94, v33
	ds_write_b32 v95, v35 offset:36928
	v_cndmask_b32_e32 v36, v38, v36, vcc
	v_mul_f32_e64 v38, -v36, s44
	v_cmp_lt_f32_e32 vcc, s43, v36
	s_nop 1
	v_cndmask_b32_e64 v36, -v36, v38, vcc
	v_sqrt_f32_e32 v38, v36
	s_nop 0
	v_add_u32_e32 v33, -1, v38
	v_fma_f32 v35, -v33, v38, v36
	v_cmp_ge_f32_e64 s[10:11], 0, v35
	v_add_u32_e32 v35, 1, v38
	s_nop 0
	v_cndmask_b32_e64 v33, v38, v33, s[10:11]
	v_fma_f32 v38, -v35, v38, v36
	v_cmp_lt_f32_e64 s[10:11], 0, v38
	s_nop 1
	v_cndmask_b32_e64 v33, v33, v35, s[10:11]
	v_mul_f32_e32 v35, 0x37800000, v33
	v_cndmask_b32_e32 v33, v33, v35, vcc
	v_cmp_class_f32_e32 vcc, v36, v135
	v_lshlrev_b32_e32 v35, 16, v172
	s_nop 0
	v_cndmask_b32_e32 v33, v33, v36, vcc
	v_mul_f32_e32 v33, v60, v33
	v_mul_f32_e32 v33, v33, v35
	ds_write_b32 v96, v33
	ds_read_b128 v[154:157], v97
	ds_read_b128 v[160:163], v97 offset:64
	ds_read_b128 v[164:167], v97 offset:9216
	ds_read_b128 v[168:171], v97 offset:9280
	s_waitcnt lgkmcnt(3)
	v_mfma_f32_16x16x32_bf16 v[154:157], v[24:27], v[154:157], 0
	s_waitcnt lgkmcnt(1)
	v_mfma_f32_16x16x32_bf16 v[164:167], v[24:27], v[164:167], 0
	v_mfma_f32_16x16x32_bf16 v[154:157], v[28:31], v[160:163], v[154:157]
	s_waitcnt lgkmcnt(0)
	v_mfma_f32_16x16x32_bf16 v[160:163], v[28:31], v[168:171], v[164:167]
	s_nop 5
	v_add_f32_e32 v33, v148, v154
	v_mul_f32_e32 v33, 0xbfb8aa3b, v33
	v_exp_f32_e32 v38, v33
	v_add_f32_e32 v33, v149, v160
	v_mul_f32_e32 v33, 0xbfb8aa3b, v33
	v_exp_f32_e32 v39, v33
	v_add_f32_e32 v33, v148, v155
	v_mul_f32_e32 v33, 0xbfb8aa3b, v33
	v_exp_f32_e32 v62, v33
	v_add_f32_e32 v33, v149, v161
	v_mul_f32_e32 v33, 0xbfb8aa3b, v33
	v_exp_f32_e32 v63, v33
	v_pk_add_f32 v[38:39], v[38:39], 1.0 op_sel_hi:[1,0]
	v_pk_add_f32 v[62:63], v[62:63], 1.0 op_sel_hi:[1,0]
	v_mul_f32_e32 v33, v38, v39
	v_rcp_f32_e32 v155, v33
	v_mul_f32_e32 v33, v62, v63
	v_rcp_f32_e32 v154, v33
	v_mul_f32_e32 v33, v38, v155
	v_mov_b32_e32 v38, v63
	v_pk_mul_f32 v[38:39], v[38:39], v[154:155]
	v_mul_f32_e32 v47, v62, v154
	v_pk_mul_f32 v[38:39], v[38:39], s[14:15] op_sel_hi:[1,0]
	s_nop 0
	v_pk_mul_f32 v[38:39], v[56:57], v[38:39]
	s_nop 0
	v_mul_f32_e32 v35, 0x3fb8aa3b, v39
	v_exp_f32_e32 v35, v35
	v_pk_add_f32 v[160:161], v[38:39], v[38:39]
	v_fma_f32 v39, v35, v35, -1.0
	v_fma_f32 v36, v161, s41, 0.5
	v_fma_f32 v36, v161, v36, 1.0
	v_mul_f32_e32 v36, v161, v36
	v_cmp_lt_f32_e32 vcc, s42, v161
	ds_write_b32 v89, v35 offset:36992
	s_nop 0
	v_cndmask_b32_e32 v36, v39, v36, vcc
	v_mul_f32_e64 v39, -v36, s44
	v_cmp_lt_f32_e32 vcc, s43, v36
	s_nop 1
	v_cndmask_b32_e64 v36, -v36, v39, vcc
	v_sqrt_f32_e32 v39, v36
	s_nop 0
	v_add_u32_e32 v35, -1, v39
	v_fma_f32 v60, -v35, v39, v36
	v_cmp_ge_f32_e64 s[10:11], 0, v60
	v_add_u32_e32 v60, 1, v39
	s_nop 0
	v_cndmask_b32_e64 v35, v39, v35, s[10:11]
	v_fma_f32 v39, -v60, v39, v36
	v_cmp_lt_f32_e64 s[10:11], 0, v39
	s_nop 1
	v_cndmask_b32_e64 v35, v35, v60, s[10:11]
	v_mul_f32_e32 v39, 0x37800000, v35
	v_cndmask_b32_e32 v35, v35, v39, vcc
	v_cmp_class_f32_e32 vcc, v36, v135
	s_nop 1
	v_cndmask_b32_e32 v35, v35, v36, vcc
	v_mul_f32_e32 v33, v33, v35
	v_mul_f32_e32 v35, 0x3fb8aa3b, v38
	v_exp_f32_e32 v35, v35
	v_fma_f32 v36, v160, s41, 0.5
	v_fma_f32 v36, v160, v36, 1.0
	v_mul_f32_e32 v36, v160, v36
	v_fma_f32 v38, v35, v35, -1.0
	v_cmp_lt_f32_e32 vcc, s42, v160
	v_mul_f32_e32 v33, v33, v37
	ds_write_b32 v98, v33
	ds_write_b32 v91, v35 offset:36992
	v_cndmask_b32_e32 v36, v38, v36, vcc
	v_mul_f32_e64 v38, -v36, s44
	v_cmp_lt_f32_e32 vcc, s43, v36
	s_nop 1
	v_cndmask_b32_e64 v36, -v36, v38, vcc
	v_sqrt_f32_e32 v38, v36
	s_nop 0
	v_add_u32_e32 v33, -1, v38
	v_fma_f32 v35, -v33, v38, v36
	v_cmp_ge_f32_e64 s[10:11], 0, v35
	v_add_u32_e32 v35, 1, v38
	v_fma_f32 v37, -v35, v38, v36
	v_cndmask_b32_e64 v33, v38, v33, s[10:11]
	v_cmp_lt_f32_e64 s[10:11], 0, v37
	s_nop 1
	v_cndmask_b32_e64 v33, v33, v35, s[10:11]
	v_mul_f32_e32 v35, 0x37800000, v33
	v_cndmask_b32_e32 v33, v33, v35, vcc
	v_cmp_class_f32_e32 vcc, v36, v135
	v_lshlrev_b32_e32 v35, 16, v49
	s_nop 0
	v_cndmask_b32_e32 v33, v33, v36, vcc
	v_mul_f32_e32 v33, v47, v33
	v_mul_f32_e32 v33, v33, v35
	v_add_f32_e32 v35, v148, v156
	v_mul_f32_e32 v35, 0xbfb8aa3b, v35
	v_exp_f32_e32 v36, v35
	v_add_f32_e32 v35, v149, v162
	v_mul_f32_e32 v35, 0xbfb8aa3b, v35
	v_exp_f32_e32 v37, v35
	v_add_f32_e32 v35, v148, v157
; __device__ __forceinline__ float bf2f(u16 b) { return __uint_as_float(((unsigned)b) << 16); }
; __device__ __forceinline__ void lru_phase(const Args& A, unsigned char* smem, const bool dry) {
;     ...
;                     for (int dt = 0; dt < 4; ++dt) { const int d = 16 * dt + r16;
;                         f32x4 ga = (f32x4){0.f, 0.f, 0.f, 0.f}, gx = (f32x4){0.f, 0.f, 0.f, 0.f};
; #pragma unroll
;                         for (int ks = 0; ks < 2; ++ks) { const bf16x8 Ba = *(const bf16x8*)(wT + (d) * 72 + ks * 32 + q4 * 8); const bf16x8 Bx = *(const bf16x8*)(wT + (64 + d) * 72 + ks * 32 + q4 * 8);
;                             ga = __builtin_amdgcn_mfma_f32_16x16x32_bf16(Af[ks], Ba, ga, 0, 0, 0); gx = __builtin_amdgcn_mfma_f32_16x16x32_bf16(Af[ks], Bx, gx, 0, 0, 0); }
; #pragma unroll
;                         for (int j = 0; j < 4; ++j) { const int i = 16 * wave + 4 * q4 + j;
;                             const float ea = 1.0f + __expf(-(ga[j] + ba[dt])), ex = 1.0f + __expf(-(gx[j] + bx[dt])); const float rab = __builtin_amdgcn_rcpf(ea * ex);
;                             const float rg = rab * ex, ig = rab * ea;
;                             const float la = -8.0f * rg * sp[dt]; const float av = __expf(la); const float v2 = 2.0f * la;
;                             const float em = (v2 > -0.02f) ? v2 * (1.0f + v2 * (0.5f + v2 * (1.0f / 6.0f))) : (av * av - 1.0f);
;                             aL[i * 64 + d] = av; bL[i * 64 + d] = sqrtf(-em) * ig * bf2f(ub[i * 72 + d]); } } }
	v_mul_f32_e32 v35, 0xbfb8aa3b, v35
	v_exp_f32_e32 v38, v35
	v_add_f32_e32 v35, v149, v163
	v_mul_f32_e32 v35, 0xbfb8aa3b, v35
	v_exp_f32_e32 v39, v35
	v_pk_add_f32 v[36:37], v[36:37], 1.0 op_sel_hi:[1,0]
	ds_write_b32 v99, v33
	v_mul_f32_e32 v35, v36, v37
	v_pk_add_f32 v[38:39], v[38:39], 1.0 op_sel_hi:[1,0]
	v_rcp_f32_e32 v63, v35
	v_mul_f32_e32 v35, v38, v39
	v_rcp_f32_e32 v62, v35
	v_lshlrev_b32_e32 v47, 16, v173
	v_mul_f32_e32 v33, v36, v63
	v_mov_b32_e32 v36, v39
	v_pk_mul_f32 v[36:37], v[36:37], v[62:63]
	v_mul_f32_e32 v38, v38, v62
	v_pk_mul_f32 v[36:37], v[36:37], s[14:15] op_sel_hi:[1,0]
	s_nop 0
	v_pk_mul_f32 v[36:37], v[56:57], v[36:37]
	s_nop 0
	v_mul_f32_e32 v35, 0x3fb8aa3b, v37
	v_exp_f32_e32 v35, v35
	v_pk_add_f32 v[154:155], v[36:37], v[36:37]
	v_fma_f32 v39, v35, v35, -1.0
	v_fma_f32 v37, v155, s41, 0.5
	v_fma_f32 v37, v155, v37, 1.0
	v_mul_f32_e32 v37, v155, v37
	v_cmp_lt_f32_e32 vcc, s42, v155
	ds_write_b32 v93, v35 offset:36992
	s_nop 0
	v_cndmask_b32_e32 v37, v39, v37, vcc
	v_mul_f32_e64 v39, -v37, s44
	v_cmp_lt_f32_e32 vcc, s43, v37
	s_nop 1
	v_cndmask_b32_e64 v37, -v37, v39, vcc
	v_sqrt_f32_e32 v39, v37
	s_nop 0
	v_add_u32_e32 v35, -1, v39
	v_fma_f32 v49, -v35, v39, v37
	v_cmp_ge_f32_e64 s[10:11], 0, v49
	v_add_u32_e32 v49, 1, v39
	s_nop 0
	v_cndmask_b32_e64 v35, v39, v35, s[10:11]
	v_fma_f32 v39, -v49, v39, v37
	v_cmp_lt_f32_e64 s[10:11], 0, v39
	s_nop 1
	v_cndmask_b32_e64 v35, v35, v49, s[10:11]
	v_mul_f32_e32 v39, 0x37800000, v35
	v_cndmask_b32_e32 v35, v35, v39, vcc
	v_cmp_class_f32_e32 vcc, v37, v135
	s_nop 1
	v_cndmask_b32_e32 v35, v35, v37, vcc
	v_mul_f32_e32 v33, v33, v35
	v_mul_f32_e32 v35, 0x3fb8aa3b, v36
	v_exp_f32_e32 v35, v35
	v_fma_f32 v36, v154, s41, 0.5
	v_fma_f32 v36, v154, v36, 1.0
	v_mul_f32_e32 v36, v154, v36
	v_fma_f32 v37, v35, v35, -1.0
	v_cmp_lt_f32_e32 vcc, s42, v154
	v_mul_f32_e32 v33, v33, v47
	ds_write_b32 v100, v33
	ds_write_b32 v95, v35 offset:36992
	v_cndmask_b32_e32 v36, v37, v36, vcc
	v_mul_f32_e64 v37, -v36, s44
	v_cmp_lt_f32_e32 vcc, s43, v36
	s_nop 1
	v_cndmask_b32_e64 v36, -v36, v37, vcc
	v_sqrt_f32_e32 v37, v36
	s_nop 0
	v_add_u32_e32 v33, -1, v37
	v_fma_f32 v35, -v33, v37, v36
	v_cmp_ge_f32_e64 s[10:11], 0, v35
	v_add_u32_e32 v35, 1, v37
	s_nop 0
	v_cndmask_b32_e64 v33, v37, v33, s[10:11]
	v_fma_f32 v37, -v35, v37, v36
	v_cmp_lt_f32_e64 s[10:11], 0, v37
	s_nop 1
	v_cndmask_b32_e64 v33, v33, v35, s[10:11]
	v_mul_f32_e32 v35, 0x37800000, v33
	v_cndmask_b32_e32 v33, v33, v35, vcc
	v_cmp_class_f32_e32 vcc, v36, v135
	v_lshlrev_b32_e32 v35, 16, v174
	s_nop 0
	v_cndmask_b32_e32 v33, v33, v36, vcc
	v_mul_f32_e32 v33, v38, v33
	v_mul_f32_e32 v33, v33, v35
	ds_write_b32 v101, v33
	ds_read_b128 v[36:39], v102
	ds_read_b128 v[154:157], v102 offset:64
	ds_read_b128 v[160:163], v102 offset:9216
	ds_read_b128 v[164:167], v102 offset:9280
	s_waitcnt lgkmcnt(3)
	v_mfma_f32_16x16x32_bf16 v[36:39], v[24:27], v[36:39], 0
	v_lshlrev_b32_e32 v35, 16, v159
	s_waitcnt lgkmcnt(1)
	v_mfma_f32_16x16x32_bf16 v[24:27], v[24:27], v[160:163], 0
	s_waitcnt lgkmcnt(0)
	v_mfma_f32_16x16x32_bf16 v[24:27], v[28:31], v[164:167], v[24:27]
	v_mfma_f32_16x16x32_bf16 v[36:39], v[28:31], v[154:157], v[36:39]
	s_nop 6
	v_add_f32_e32 v24, v151, v24
	v_add_f32_e32 v28, v150, v36
	v_mul_f32_e32 v24, 0xbfb8aa3b, v24
	v_mul_f32_e32 v28, 0xbfb8aa3b, v28
	v_exp_f32_e32 v29, v24
	v_add_f32_e32 v24, v150, v37
	v_add_f32_e32 v25, v151, v25
	v_exp_f32_e32 v28, v28
	v_mul_f32_e32 v24, 0xbfb8aa3b, v24
	v_mul_f32_e32 v25, 0xbfb8aa3b, v25
	v_exp_f32_e32 v24, v24
	v_exp_f32_e32 v25, v25
	v_pk_add_f32 v[28:29], v[28:29], 1.0 op_sel_hi:[1,0]
	v_add_f32_e32 v27, v151, v27
	v_mul_f32_e32 v30, v28, v29
	v_pk_add_f32 v[24:25], v[24:25], 1.0 op_sel_hi:[1,0]
	v_rcp_f32_e32 v31, v30
	v_mul_f32_e32 v30, v24, v25
	v_rcp_f32_e32 v30, v30
	v_mul_f32_e32 v27, 0xbfb8aa3b, v27
	v_mul_f32_e32 v33, v28, v31
	v_mov_b32_e32 v28, v25
	v_pk_mul_f32 v[28:29], v[28:29], v[30:31]
	v_mul_f32_e32 v24, v24, v30
	v_pk_mul_f32 v[28:29], v[28:29], s[14:15] op_sel_hi:[1,0]
	v_exp_f32_e32 v27, v27
	v_pk_mul_f32 v[28:29], v[58:59], v[28:29]
	s_nop 0
	v_mul_f32_e32 v25, 0x3fb8aa3b, v29
	v_exp_f32_e32 v25, v25
	v_pk_add_f32 v[36:37], v[28:29], v[28:29]
	v_mul_f32_e32 v28, 0x3fb8aa3b, v28
	v_fma_f32 v29, v37, s41, 0.5
	v_fma_f32 v29, v37, v29, 1.0
	v_mul_f32_e32 v29, v37, v29
	v_fma_f32 v31, v25, v25, -1.0
	v_cmp_lt_f32_e32 vcc, s42, v37
	ds_write_b32 v89, v25 offset:37056
	v_exp_f32_e32 v28, v28
	v_cndmask_b32_e32 v29, v31, v29, vcc
	v_mul_f32_e64 v31, -v29, s44
	v_cmp_lt_f32_e32 vcc, s43, v29
	s_nop 1
	v_cndmask_b32_e64 v29, -v29, v31, vcc
	v_sqrt_f32_e32 v31, v29
	s_nop 0
	v_add_u32_e32 v25, -1, v31
	v_fma_f32 v30, -v25, v31, v29
	v_cmp_ge_f32_e64 s[10:11], 0, v30
	v_add_u32_e32 v30, 1, v31
	s_nop 0
	v_cndmask_b32_e64 v25, v31, v25, s[10:11]
	v_fma_f32 v31, -v30, v31, v29
	v_cmp_lt_f32_e64 s[10:11], 0, v31
	s_nop 1
	v_cndmask_b32_e64 v25, v25, v30, s[10:11]
	v_mul_f32_e32 v30, 0x37800000, v25
	v_cndmask_b32_e32 v25, v25, v30, vcc
	v_cmp_class_f32_e32 vcc, v29, v135
	v_fma_f32 v30, v28, v28, -1.0
	s_nop 0
	v_cndmask_b32_e32 v25, v25, v29, vcc
	v_fma_f32 v29, v36, s41, 0.5
	v_fma_f32 v29, v36, v29, 1.0
	v_mul_f32_e32 v29, v36, v29
	v_cmp_lt_f32_e32 vcc, s42, v36
	v_mul_f32_e32 v25, v33, v25
	v_mul_f32_e32 v25, v25, v35
	v_cndmask_b32_e32 v29, v30, v29, vcc
	v_mul_f32_e64 v30, -v29, s44
	v_cmp_lt_f32_e32 vcc, s43, v29
	ds_write_b32 v103, v25
	ds_write_b32 v91, v28 offset:37056
	v_cndmask_b32_e64 v29, -v29, v30, vcc
	v_sqrt_f32_e32 v30, v29
	s_nop 0
	v_add_u32_e32 v25, -1, v30
	v_fma_f32 v28, -v25, v30, v29
	v_cmp_ge_f32_e64 s[10:11], 0, v28
	v_add_u32_e32 v28, 1, v30
; __device__ __forceinline__ float bf2f(u16 b) { return __uint_as_float(((unsigned)b) << 16); }
; __device__ __forceinline__ void lru_phase(const Args& A, unsigned char* smem, const bool dry) {
;     ...
;                             const float ea = 1.0f + __expf(-(ga[j] + ba[dt])), ex = 1.0f + __expf(-(gx[j] + bx[dt])); const float rab = __builtin_amdgcn_rcpf(ea * ex);
;                             const float rg = rab * ex, ig = rab * ea;
;                             const float la = -8.0f * rg * sp[dt]; const float av = __expf(la); const float v2 = 2.0f * la;
;                             const float em = (v2 > -0.02f) ? v2 * (1.0f + v2 * (0.5f + v2 * (1.0f / 6.0f))) : (av * av - 1.0f);
;                             aL[i * 64 + d] = av; bL[i * 64 + d] = sqrtf(-em) * ig * bf2f(ub[i * 72 + d]); } } }
;                 __syncthreads();
;                 float Pr[16], Hr[16];
;                 { float P = 1.f, hl = 0.f;
; #pragma unroll
;                     for (int ii = 0; ii < 16; ++ii) { const int i = 16 * wave + ii; const float av = aL[i * 64 + lane], xv = bL[i * 64 + lane]; hl = av * hl + xv; P *= av; Pr[ii] = P; Hr[ii] = hl; }
;                     segP[wave * 64 + lane] = P; segH[wave * 64 + lane] = hl; }
;                 __syncthreads();
;                 { float carry = hcar[(bt & 1) * 64 + lane];
;                     for (int w2 = 0; w2 < wave; ++w2) carry = segP[w2 * 64 + lane] * carry + segH[w2 * 64 + lane];
	s_nop 0
	v_cndmask_b32_e64 v25, v30, v25, s[10:11]
	v_fma_f32 v30, -v28, v30, v29
	v_cmp_lt_f32_e64 s[10:11], 0, v30
	s_nop 1
	v_cndmask_b32_e64 v25, v25, v28, s[10:11]
	v_mul_f32_e32 v28, 0x37800000, v25
	v_cndmask_b32_e32 v25, v25, v28, vcc
	v_cmp_class_f32_e32 vcc, v29, v135
	s_nop 1
	v_cndmask_b32_e32 v25, v25, v29, vcc
	v_mul_f32_e32 v24, v24, v25
	v_lshlrev_b32_e32 v25, 16, v61
	v_mul_f32_e32 v30, v24, v25
	v_add_f32_e32 v24, v150, v38
	v_add_f32_e32 v25, v151, v26
	v_mul_f32_e32 v24, 0xbfb8aa3b, v24
	v_mul_f32_e32 v25, 0xbfb8aa3b, v25
	v_add_f32_e32 v26, v150, v39
	v_exp_f32_e32 v24, v24
	v_exp_f32_e32 v25, v25
	v_mul_f32_e32 v26, 0xbfb8aa3b, v26
	v_exp_f32_e32 v26, v26
	ds_write_b32 v104, v30
	v_pk_add_f32 v[24:25], v[24:25], 1.0 op_sel_hi:[1,0]
	v_pk_add_f32 v[26:27], v[26:27], 1.0 op_sel_hi:[1,0]
	v_mul_f32_e32 v28, v24, v25
	v_rcp_f32_e32 v29, v28
	v_mul_f32_e32 v28, v26, v27
	v_rcp_f32_e32 v28, v28
	v_mul_f32_e32 v33, v24, v29
	v_mov_b32_e32 v24, v27
	v_pk_mul_f32 v[24:25], v[24:25], v[28:29]
	v_mul_f32_e32 v26, v26, v28
	v_pk_mul_f32 v[24:25], v[24:25], s[14:15] op_sel_hi:[1,0]
	s_nop 0
	v_pk_mul_f32 v[24:25], v[58:59], v[24:25]
	s_nop 0
	v_mul_f32_e32 v27, 0x3fb8aa3b, v25
	v_exp_f32_e32 v27, v27
	v_pk_add_f32 v[30:31], v[24:25], v[24:25]
	v_mul_f32_e32 v24, 0x3fb8aa3b, v24
	v_fma_f32 v25, v31, s41, 0.5
	v_fma_f32 v25, v31, v25, 1.0
	v_mul_f32_e32 v25, v31, v25
	v_fma_f32 v29, v27, v27, -1.0
	v_cmp_lt_f32_e32 vcc, s42, v31
	ds_write_b32 v93, v27 offset:37056
	v_exp_f32_e32 v24, v24
	v_cndmask_b32_e32 v25, v29, v25, vcc
	v_mul_f32_e64 v29, -v25, s44
	v_cmp_lt_f32_e32 vcc, s43, v25
	v_lshlrev_b32_e32 v31, 16, v34
	s_nop 0
	v_cndmask_b32_e64 v25, -v25, v29, vcc
	v_sqrt_f32_e32 v29, v25
	s_nop 0
	v_add_u32_e32 v27, -1, v29
	v_fma_f32 v28, -v27, v29, v25
	v_cmp_ge_f32_e64 s[10:11], 0, v28
	v_add_u32_e32 v28, 1, v29
	s_nop 0
	v_cndmask_b32_e64 v27, v29, v27, s[10:11]
	v_fma_f32 v29, -v28, v29, v25
	v_cmp_lt_f32_e64 s[10:11], 0, v29
	s_nop 1
	v_cndmask_b32_e64 v27, v27, v28, s[10:11]
	v_mul_f32_e32 v28, 0x37800000, v27
	v_cndmask_b32_e32 v27, v27, v28, vcc
	v_cmp_class_f32_e32 vcc, v25, v135
	v_fma_f32 v28, v24, v24, -1.0
	s_nop 0
	v_cndmask_b32_e32 v25, v27, v25, vcc
	v_fma_f32 v27, v30, s41, 0.5
	v_fma_f32 v27, v30, v27, 1.0
	v_mul_f32_e32 v27, v30, v27
	v_cmp_lt_f32_e32 vcc, s42, v30
	v_mul_f32_e32 v25, v33, v25
	v_mul_f32_e32 v25, v25, v31
	v_cndmask_b32_e32 v27, v28, v27, vcc
	v_mul_f32_e64 v28, -v27, s44
	v_cmp_lt_f32_e32 vcc, s43, v27
	ds_write_b32 v105, v25
	ds_write_b32 v95, v24 offset:37056
	v_cndmask_b32_e64 v27, -v27, v28, vcc
	v_sqrt_f32_e32 v28, v27
	s_nop 0
	v_add_u32_e32 v24, -1, v28
	v_fma_f32 v25, -v24, v28, v27
	v_cmp_ge_f32_e64 s[10:11], 0, v25
	v_add_u32_e32 v25, 1, v28
	s_nop 0
	v_cndmask_b32_e64 v24, v28, v24, s[10:11]
	v_fma_f32 v28, -v25, v28, v27
	v_cmp_lt_f32_e64 s[10:11], 0, v28
	s_nop 1
	v_cndmask_b32_e64 v24, v24, v25, s[10:11]
	v_mul_f32_e32 v25, 0x37800000, v24
	v_cndmask_b32_e32 v24, v24, v25, vcc
	v_cmp_class_f32_e32 vcc, v27, v135
	v_lshlrev_b32_e32 v25, 16, v32
	s_lshl_b32 s10, s49, 8
	v_cndmask_b32_e32 v24, v24, v27, vcc
	v_mul_f32_e32 v24, v26, v24
	v_mul_f32_e32 v24, v24, v25
	ds_write_b32 v106, v24
	s_waitcnt lgkmcnt(0)
	s_barrier
	ds_read2st64_b32 v[24:25], v107 offset0:144 offset1:145
	ds_read2st64_b32 v[26:27], v107 offset0:146 offset1:147
	ds_read2st64_b32 v[28:29], v107 offset0:148 offset1:149
	ds_read2st64_b32 v[30:31], v107 offset0:150 offset1:151
	ds_read_b32 v163, v108
	ds_read_b32 v161, v109
	ds_read_b32 v159, v110
	ds_read_b32 v157, v111
	ds_read_b32 v155, v112
	ds_read_b32 v63, v113
	ds_read_b32 v60, v114
	ds_read_b32 v39, v115
	s_waitcnt lgkmcnt(7)
	v_fmac_f32_e32 v163, 0, v24
	v_mul_f32_e32 v164, v24, v25
	s_waitcnt lgkmcnt(6)
	v_fmac_f32_e32 v161, v163, v25
	v_mul_f32_e32 v162, v164, v26
	s_waitcnt lgkmcnt(5)
	v_fmac_f32_e32 v159, v161, v26
	v_mul_f32_e32 v160, v162, v27
	s_waitcnt lgkmcnt(4)
	v_fmac_f32_e32 v157, v159, v27
	v_mul_f32_e32 v158, v160, v28
	s_waitcnt lgkmcnt(3)
	v_fmac_f32_e32 v155, v157, v28
	v_mul_f32_e32 v156, v158, v29
	s_waitcnt lgkmcnt(2)
	v_fmac_f32_e32 v63, v155, v29
	v_mul_f32_e32 v154, v156, v30
	s_waitcnt lgkmcnt(1)
	v_fmac_f32_e32 v60, v63, v30
	v_mul_f32_e32 v61, v154, v31
	s_waitcnt lgkmcnt(0)
	v_fmac_f32_e32 v39, v60, v31
	ds_read2st64_b32 v[166:167], v107 offset0:152 offset1:153
	ds_read2st64_b32 v[168:169], v107 offset0:154 offset1:155
	ds_read2st64_b32 v[170:171], v107 offset0:156 offset1:157
	ds_read2st64_b32 v[172:173], v107 offset0:158 offset1:159
	ds_read_b32 v47, v116
	ds_read_b32 v37, v117
	ds_read_b32 v35, v118
	ds_read_b32 v33, v119
	ds_read_b32 v31, v120
	ds_read_b32 v29, v121
	ds_read_b32 v27, v122
	ds_read_b32 v26, v123
	s_waitcnt lgkmcnt(11)
	v_mul_f32_e32 v62, v61, v166
	s_waitcnt lgkmcnt(7)
	v_fmac_f32_e32 v47, v39, v166
	v_mul_f32_e32 v49, v62, v167
	s_waitcnt lgkmcnt(6)
	v_fmac_f32_e32 v37, v47, v167
	v_mul_f32_e32 v38, v49, v168
	s_waitcnt lgkmcnt(5)
	v_fmac_f32_e32 v35, v37, v168
	v_mul_f32_e32 v36, v38, v169
	s_waitcnt lgkmcnt(4)
	v_fmac_f32_e32 v33, v35, v169
	v_mul_f32_e32 v34, v36, v170
	s_waitcnt lgkmcnt(3)
	v_fmac_f32_e32 v31, v33, v170
	v_mul_f32_e32 v32, v34, v171
	s_waitcnt lgkmcnt(2)
	v_fmac_f32_e32 v29, v31, v171
	v_mul_f32_e32 v30, v32, v172
	s_and_b32 s10, s10, 0x100
	s_waitcnt lgkmcnt(1)
	v_fmac_f32_e32 v27, v29, v172
	v_mul_f32_e32 v28, v30, v173
	v_add_u32_e32 v25, s10, v68
	s_waitcnt lgkmcnt(0)
	v_fmac_f32_e32 v26, v27, v173
	ds_write_b32 v66, v28
	ds_write_b32 v67, v26
	s_waitcnt lgkmcnt(0)
	s_barrier
	ds_read_b32 v25, v25
	v_add_u32_e32 v167, 0xfffff800, v131
	ds_read_b32 v228, v167
	ds_read_b32 v236, v131
	ds_read_b32 v229, v167 offset:256
	ds_read_b32 v237, v131 offset:256
	ds_read_b32 v230, v167 offset:512
	ds_read_b32 v238, v131 offset:512
	ds_read_b32 v231, v167 offset:768
	ds_read_b32 v239, v131 offset:768
	ds_read_b32 v232, v167 offset:1024
	ds_read_b32 v240, v131 offset:1024
	ds_read_b32 v233, v167 offset:1280
	ds_read_b32 v241, v131 offset:1280
	ds_read_b32 v234, v167 offset:1536
	ds_read_b32 v242, v131 offset:1536
	s_waitcnt lgkmcnt(0)
	v_cmp_lt_u32_e32 vcc, 0, v81
	v_fma_f32 v243, v25, v228, v236
	s_nop 0
	v_cndmask_b32_e32 v25, v25, v243, vcc
	v_cmp_lt_u32_e32 vcc, 1, v81
	v_fma_f32 v243, v25, v229, v237
	s_nop 0
	v_cndmask_b32_e32 v25, v25, v243, vcc
	v_cmp_lt_u32_e32 vcc, 2, v81
	v_fma_f32 v243, v25, v230, v238
	s_nop 0
	v_cndmask_b32_e32 v25, v25, v243, vcc
	v_cmp_lt_u32_e32 vcc, 3, v81
	v_fma_f32 v243, v25, v231, v239
	s_nop 0
	v_cndmask_b32_e32 v25, v25, v243, vcc
	v_cmp_lt_u32_e32 vcc, 4, v81
	v_fma_f32 v243, v25, v232, v240
	s_nop 0
	v_cndmask_b32_e32 v25, v25, v243, vcc
	v_cmp_lt_u32_e32 vcc, 5, v81
	v_fma_f32 v243, v25, v233, v241
	s_nop 0
	v_cndmask_b32_e32 v25, v25, v243, vcc
	v_cmp_lt_u32_e32 vcc, 6, v81
	v_fma_f32 v243, v25, v234, v242
	s_nop 0
	v_cndmask_b32_e32 v25, v25, v243, vcc
